# v10 + grid seams: non-leader workgroups poll the top-level generation word directly instead of waiting for their XCD leader to republish it
# speedup vs baseline: 1.0069x; 1.0040x over previous
; __device__ __forceinline__ unsigned xb_ld(unsigned* p)              { return __hip_atomic_load(p, __ATOMIC_RELAXED, __HIP_MEMORY_SCOPE_AGENT); }
; __device__ __forceinline__ unsigned xb_add(unsigned* p, unsigned v) { return __hip_atomic_fetch_add(p, v, __ATOMIC_RELAXED, __HIP_MEMORY_SCOPE_AGENT); }
; #define XB_SPIN(cond, bar) do { unsigned _sp = 0; while (cond) { __builtin_amdgcn_s_sleep(1); \
;     if ((++_sp & 255u) == 0u) { if (xb_ld(&(bar)[XB_TMO])) break; if (_sp > XB_SPIN_CAP) { atomicAdd(&(bar)[XB_TMO], 1u); break; } } } } while (0)
; __device__ __forceinline__ void xcd_barrier(const XcdBarrier& b) {
;     ...
;         const unsigned old = xb_add(&bar[XB_XSUB(b.x)], 1u);
;         const unsigned gen = old / nloc;
;         if (old + 1u == (gen + 1u) * nloc) {
;             __builtin_amdgcn_fence(__ATOMIC_RELEASE, "agent");
;             asm volatile("s_waitcnt vmcnt(0)" ::: "memory");
;             const unsigned og = xb_add(&bar[XB_TOP], 1u);
;             const unsigned tg = og / nx;
;             if (og + 1u == (tg + 1u) * nx) xb_add(&bar[XB_TOPGEN], 1u);
;             else XB_SPIN(xb_ld(&bar[XB_TOPGEN]) == tg, bar);
;             __builtin_amdgcn_fence(__ATOMIC_ACQUIRE, "agent");
;             xb_add(&bar[XB_XGEN(b.x)], 1u);
;             asm volatile("s_waitcnt vmcnt(0)" ::: "memory");
;         } else {
;             XB_SPIN(xb_ld(&bar[XB_XGEN(b.x)]) == gen, bar);
;             __builtin_amdgcn_fence(__ATOMIC_ACQUIRE, "agent");
.LBB0_144:
	s_or_b64 exec, exec, s[12:13]
	v_cvt_f32_u32_e32 v5, v3
	s_waitcnt vmcnt(0)
	v_readfirstlane_b32 s0, v4
	v_sub_u32_e32 v4, 0, v3
	v_rcp_iflag_f32_e32 v5, v5
	v_add_u32_e32 v6, s0, v2
	v_mul_f32_e32 v5, 0x4f7ffffe, v5
	v_cvt_u32_f32_e32 v5, v5
	v_mul_lo_u32 v2, v4, v5
	v_mul_hi_u32 v2, v5, v2
	v_add_u32_e32 v2, v5, v2
	v_mul_hi_u32 v2, v6, v2
	v_mul_lo_u32 v4, v2, v3
	v_sub_u32_e32 v4, v6, v4
	v_add_u32_e32 v5, 1, v2
	v_cmp_ge_u32_e32 vcc, v4, v3
	s_nop 1
	v_cndmask_b32_e32 v2, v2, v5, vcc
	v_sub_u32_e32 v5, v4, v3
	v_cndmask_b32_e32 v4, v4, v5, vcc
	v_add_u32_e32 v5, 1, v2
	v_cmp_ge_u32_e32 vcc, v4, v3
	v_add_u32_e32 v4, 1, v6
	s_nop 0
	v_cndmask_b32_e32 v2, v2, v5, vcc
	v_mul_lo_u32 v5, v3, v2
	v_add_u32_e32 v3, v5, v3
	v_cmp_ne_u32_e32 vcc, v4, v3
	s_and_saveexec_b64 s[0:1], vcc
	s_xor_b64 s[8:9], exec, s[0:1]
	s_cbranch_execz .LBB0_158
	s_waitcnt lgkmcnt(0)
	v_mov_b32_e32 v1, 0
	s_add_u32 s16, s78, 0xbd03500
	s_addc_u32 s17, s79, 0
	global_load_dword v1, v1, s[16:17] sc1
	s_waitcnt vmcnt(0)
	v_cmp_eq_u32_e32 vcc, v1, v2
	s_and_saveexec_b64 s[12:13], vcc
	s_cbranch_execz .LBB0_157
	s_add_u32 s14, s78, 0xbd00200
	s_addc_u32 s15, s79, 0
	s_mov_b32 s0, 1
	s_mov_b64 s[18:19], 0
	v_mov_b32_e32 v1, 0
	s_branch .LBB0_148

; __device__ __forceinline__ unsigned xb_ld(unsigned* p)              { return __hip_atomic_load(p, __ATOMIC_RELAXED, __HIP_MEMORY_SCOPE_AGENT); }
; __device__ __forceinline__ unsigned xb_add(unsigned* p, unsigned v) { return __hip_atomic_fetch_add(p, v, __ATOMIC_RELAXED, __HIP_MEMORY_SCOPE_AGENT); }
; #define XB_SPIN(cond, bar) do { unsigned _sp = 0; while (cond) { __builtin_amdgcn_s_sleep(1); \
;     if ((++_sp & 255u) == 0u) { if (xb_ld(&(bar)[XB_TMO])) break; if (_sp > XB_SPIN_CAP) { atomicAdd(&(bar)[XB_TMO], 1u); break; } } } } while (0)
; __device__ __forceinline__ void xcd_barrier(const XcdBarrier& b) {
;     ...
;         const unsigned old = xb_add(&bar[XB_XSUB(b.x)], 1u);
;         const unsigned gen = old / nloc;
;         if (old + 1u == (gen + 1u) * nloc) {
;             __builtin_amdgcn_fence(__ATOMIC_RELEASE, "agent");
;             asm volatile("s_waitcnt vmcnt(0)" ::: "memory");
;             const unsigned og = xb_add(&bar[XB_TOP], 1u);
;             const unsigned tg = og / nx;
;             if (og + 1u == (tg + 1u) * nx) xb_add(&bar[XB_TOPGEN], 1u);
;             else XB_SPIN(xb_ld(&bar[XB_TOPGEN]) == tg, bar);
;             __builtin_amdgcn_fence(__ATOMIC_ACQUIRE, "agent");
;             xb_add(&bar[XB_XGEN(b.x)], 1u);
;             asm volatile("s_waitcnt vmcnt(0)" ::: "memory");
;         } else {
;             XB_SPIN(xb_ld(&bar[XB_XGEN(b.x)]) == gen, bar);
.LBB0_247:
	s_or_b64 exec, exec, s[22:23]
	v_cvt_f32_u32_e32 v6, v4
	s_waitcnt vmcnt(0)
	v_readfirstlane_b32 s0, v5
	v_sub_u32_e32 v5, 0, v4
	v_rcp_iflag_f32_e32 v6, v6
	v_add_u32_e32 v7, s0, v3
	v_mul_f32_e32 v6, 0x4f7ffffe, v6
	v_cvt_u32_f32_e32 v6, v6
	v_mul_lo_u32 v3, v5, v6
	v_mul_hi_u32 v3, v6, v3
	v_add_u32_e32 v3, v6, v3
	v_mul_hi_u32 v3, v7, v3
	v_mul_lo_u32 v5, v3, v4
	v_sub_u32_e32 v5, v7, v5
	v_add_u32_e32 v6, 1, v3
	v_cmp_ge_u32_e32 vcc, v5, v4
	s_nop 1
	v_cndmask_b32_e32 v3, v3, v6, vcc
	v_sub_u32_e32 v6, v5, v4
	v_cndmask_b32_e32 v5, v5, v6, vcc
	v_add_u32_e32 v6, 1, v3
	v_cmp_ge_u32_e32 vcc, v5, v4
	v_add_u32_e32 v5, 1, v7
	s_nop 0
	v_cndmask_b32_e32 v3, v3, v6, vcc
	v_mul_lo_u32 v6, v4, v3
	v_add_u32_e32 v4, v6, v4
	v_cmp_ne_u32_e32 vcc, v5, v4
	s_and_saveexec_b64 s[0:1], vcc
	s_xor_b64 s[20:21], exec, s[0:1]
	s_cbranch_execz .LBB0_261
	s_waitcnt lgkmcnt(0)
	v_mov_b32_e32 v2, 0
	s_add_u32 s26, s78, 0xbd03500
	s_addc_u32 s27, s79, 0
	global_load_dword v2, v2, s[26:27] sc1
	s_waitcnt vmcnt(0)
	v_cmp_eq_u32_e32 vcc, v2, v3
	s_and_saveexec_b64 s[22:23], vcc
	s_cbranch_execz .LBB0_260
	s_add_u32 s24, s78, 0xbd00200
	s_addc_u32 s25, s79, 0
	s_mov_b32 s0, 1
	s_mov_b64 s[28:29], 0
	v_mov_b32_e32 v2, 0
	s_branch .LBB0_251

; __device__ __forceinline__ unsigned xb_ld(unsigned* p)              { return __hip_atomic_load(p, __ATOMIC_RELAXED, __HIP_MEMORY_SCOPE_AGENT); }
; __device__ __forceinline__ unsigned xb_add(unsigned* p, unsigned v) { return __hip_atomic_fetch_add(p, v, __ATOMIC_RELAXED, __HIP_MEMORY_SCOPE_AGENT); }
; #define XB_SPIN(cond, bar) do { unsigned _sp = 0; while (cond) { __builtin_amdgcn_s_sleep(1); \
;     if ((++_sp & 255u) == 0u) { if (xb_ld(&(bar)[XB_TMO])) break; if (_sp > XB_SPIN_CAP) { atomicAdd(&(bar)[XB_TMO], 1u); break; } } } } while (0)
; __device__ __forceinline__ void xcd_barrier(const XcdBarrier& b) {
;     ...
;         const unsigned old = xb_add(&bar[XB_XSUB(b.x)], 1u);
;         const unsigned gen = old / nloc;
;         if (old + 1u == (gen + 1u) * nloc) {
;             __builtin_amdgcn_fence(__ATOMIC_RELEASE, "agent");
;             asm volatile("s_waitcnt vmcnt(0)" ::: "memory");
;             const unsigned og = xb_add(&bar[XB_TOP], 1u);
;             const unsigned tg = og / nx;
;             if (og + 1u == (tg + 1u) * nx) xb_add(&bar[XB_TOPGEN], 1u);
;             else XB_SPIN(xb_ld(&bar[XB_TOPGEN]) == tg, bar);
;             __builtin_amdgcn_fence(__ATOMIC_ACQUIRE, "agent");
;             xb_add(&bar[XB_XGEN(b.x)], 1u);
;             asm volatile("s_waitcnt vmcnt(0)" ::: "memory");
;         } else {
;             XB_SPIN(xb_ld(&bar[XB_XGEN(b.x)]) == gen, bar);
.LBB0_438:
	s_or_b64 exec, exec, s[10:11]
	v_cvt_f32_u32_e32 v6, v4
	s_waitcnt vmcnt(0)
	v_readfirstlane_b32 s0, v5
	v_sub_u32_e32 v5, 0, v4
	v_rcp_iflag_f32_e32 v6, v6
	v_add_u32_e32 v7, s0, v3
	v_mul_f32_e32 v6, 0x4f7ffffe, v6
	v_cvt_u32_f32_e32 v6, v6
	v_mul_lo_u32 v3, v5, v6
	v_mul_hi_u32 v3, v6, v3
	v_add_u32_e32 v3, v6, v3
	v_mul_hi_u32 v3, v7, v3
	v_mul_lo_u32 v5, v3, v4
	v_sub_u32_e32 v5, v7, v5
	v_add_u32_e32 v6, 1, v3
	v_cmp_ge_u32_e32 vcc, v5, v4
	s_nop 1
	v_cndmask_b32_e32 v3, v3, v6, vcc
	v_sub_u32_e32 v6, v5, v4
	v_cndmask_b32_e32 v5, v5, v6, vcc
	v_add_u32_e32 v6, 1, v3
	v_cmp_ge_u32_e32 vcc, v5, v4
	v_add_u32_e32 v5, 1, v7
	s_nop 0
	v_cndmask_b32_e32 v3, v3, v6, vcc
	v_mul_lo_u32 v6, v4, v3
	v_add_u32_e32 v4, v6, v4
	v_cmp_ne_u32_e32 vcc, v5, v4
	s_and_saveexec_b64 s[0:1], vcc
	s_xor_b64 s[8:9], exec, s[0:1]
	s_cbranch_execz .LBB0_452
	s_waitcnt lgkmcnt(0)
	v_mov_b32_e32 v2, 0
	s_add_u32 s14, s78, 0xbd03500
	s_addc_u32 s15, s79, 0
	global_load_dword v2, v2, s[14:15] sc1
	s_waitcnt vmcnt(0)
	v_cmp_eq_u32_e32 vcc, v2, v3
	s_and_saveexec_b64 s[10:11], vcc
	s_cbranch_execz .LBB0_451
	s_add_u32 s12, s78, 0xbd00200
	s_addc_u32 s13, s79, 0
	s_mov_b32 s0, 1
	s_mov_b64 s[16:17], 0
	v_mov_b32_e32 v2, 0
	s_branch .LBB0_442

; __device__ __forceinline__ unsigned xb_ld(unsigned* p)              { return __hip_atomic_load(p, __ATOMIC_RELAXED, __HIP_MEMORY_SCOPE_AGENT); }
; __device__ __forceinline__ unsigned xb_add(unsigned* p, unsigned v) { return __hip_atomic_fetch_add(p, v, __ATOMIC_RELAXED, __HIP_MEMORY_SCOPE_AGENT); }
; #define XB_SPIN(cond, bar) do { unsigned _sp = 0; while (cond) { __builtin_amdgcn_s_sleep(1); \
;     if ((++_sp & 255u) == 0u) { if (xb_ld(&(bar)[XB_TMO])) break; if (_sp > XB_SPIN_CAP) { atomicAdd(&(bar)[XB_TMO], 1u); break; } } } } while (0)
; __device__ __forceinline__ void xcd_barrier(const XcdBarrier& b) {
;     ...
;         const unsigned old = xb_add(&bar[XB_XSUB(b.x)], 1u);
;         const unsigned gen = old / nloc;
;         if (old + 1u == (gen + 1u) * nloc) {
;             __builtin_amdgcn_fence(__ATOMIC_RELEASE, "agent");
;             asm volatile("s_waitcnt vmcnt(0)" ::: "memory");
;             const unsigned og = xb_add(&bar[XB_TOP], 1u);
;             const unsigned tg = og / nx;
;             if (og + 1u == (tg + 1u) * nx) xb_add(&bar[XB_TOPGEN], 1u);
;             else XB_SPIN(xb_ld(&bar[XB_TOPGEN]) == tg, bar);
;             __builtin_amdgcn_fence(__ATOMIC_ACQUIRE, "agent");
;             xb_add(&bar[XB_XGEN(b.x)], 1u);
;             asm volatile("s_waitcnt vmcnt(0)" ::: "memory");
;         } else {
;             XB_SPIN(xb_ld(&bar[XB_XGEN(b.x)]) == gen, bar);
.LBB0_533:
	s_or_b64 exec, exec, s[12:13]
	v_cvt_f32_u32_e32 v132, v130
	s_waitcnt vmcnt(0)
	v_readfirstlane_b32 s4, v131
	v_sub_u32_e32 v131, 0, v130
	v_rcp_iflag_f32_e32 v132, v132
	v_add_u32_e32 v133, s4, v129
	v_mul_f32_e32 v132, 0x4f7ffffe, v132
	v_cvt_u32_f32_e32 v132, v132
	v_mul_lo_u32 v129, v131, v132
	v_mul_hi_u32 v129, v132, v129
	v_add_u32_e32 v129, v132, v129
	v_mul_hi_u32 v129, v133, v129
	v_mul_lo_u32 v131, v129, v130
	v_sub_u32_e32 v131, v133, v131
	v_add_u32_e32 v132, 1, v129
	v_cmp_ge_u32_e32 vcc, v131, v130
	s_nop 1
	v_cndmask_b32_e32 v129, v129, v132, vcc
	v_sub_u32_e32 v132, v131, v130
	v_cndmask_b32_e32 v131, v131, v132, vcc
	v_add_u32_e32 v132, 1, v129
	v_cmp_ge_u32_e32 vcc, v131, v130
	v_add_u32_e32 v131, 1, v133
	s_nop 0
	v_cndmask_b32_e32 v129, v129, v132, vcc
	v_mul_lo_u32 v132, v130, v129
	v_add_u32_e32 v130, v132, v130
	v_cmp_ne_u32_e32 vcc, v131, v130
	s_and_saveexec_b64 s[4:5], vcc
	s_xor_b64 s[4:5], exec, s[4:5]
	s_cbranch_execz .LBB0_547
	s_waitcnt lgkmcnt(0)
	v_mov_b32_e32 v128, 0
	s_add_u32 s16, s78, 0xbd03500
	s_addc_u32 s17, s79, 0
	global_load_dword v128, v128, s[16:17] sc1
	s_waitcnt vmcnt(0)
	v_cmp_eq_u32_e32 vcc, v128, v129
	s_and_saveexec_b64 s[12:13], vcc
	s_cbranch_execz .LBB0_546
	s_add_u32 s14, s78, 0xbd00200
	s_addc_u32 s15, s79, 0
	s_mov_b32 s28, 1
	s_mov_b64 s[18:19], 0
	v_mov_b32_e32 v128, 0
	s_branch .LBB0_537
